# mlstmA: K/V tile loads hoisted ahead of the conv loads (in flight during wave-0 gate chain)
# baseline (speedup 1.0000x reference)
; DI void conv_unit(const u16* __restrict__ PM, const float* __restrict__ conv_w, const float* __restrict__ conv_b, int b, int sl0, int ch, float scale, float* a8) {
;   { const float4 b0 = *(const float4*)(conv_b + ch), b1 = *(const float4*)(conv_b + ch + 4); a8[0] = b0.x; a8[1] = b0.y; a8[2] = b0.z; a8[3] = b0.w; a8[4] = b1.x; a8[5] = b1.y; a8[6] = b1.z; a8[7] = b1.w; }
; #pragma unroll
;   for (int j = 0; j < 4; ++j) {
;     const int sl = sl0 - 3 + j;
;     if (sl >= 0) {
;       const uint4 raw = *(const uint4*)(PM + ((size_t)b * SEQ + sl) * 1024 + ch);
;       float x8[8]; unpack8(raw, x8);
;       const float4 w0 = *(const float4*)(conv_w + j * 1024 + ch), w1 = *(const float4*)(conv_w + j * 1024 + ch + 4);
; DI void mlstmA_item(const Params& p, char* lds, int item) {
;     ...
;   for (int i = 0; i < 2; ++i) {
;     const int q = tid + 512 * i, e = q >> 3, s8 = (q & 7) * 8;
;     *(uint4*)(VTs + e * 72 + s8) = *(const uint4*)(VTm + ((size_t)(bh * 128 + e)) * SEQ + c * 64 + s8);
.LBB0_324:
	v_readfirstlane_b32 s72, v222
	s_nop 3
	s_cmp_lt_u32 s72, 64
	s_cbranch_scc1 .Lma_noissue
	v_add_u32_e32 v240, 0x200, v222
	s_and_b32 s73, s10, 0xffffff80
	v_lshlrev_b32_e32 v241, 4, v222
	v_ashrrev_i32_e32 v242, 3, v222
	v_ashrrev_i32_e32 v244, 3, v240
	v_and_b32_e32 v246, 0x70, v241
	v_mov_b32_e32 v247, 0
	v_add_u32_e32 v242, s73, v242
	v_add_u32_e32 v244, s73, v244
	s_and_b32 s78, s10, 0x7f
	s_lshl_b32 s78, s78, 7
	v_mov_b32_e32 v248, s78
	v_mov_b32_e32 v249, 0
	v_lshl_add_u64 v[248:249], s[6:7], 0, v[248:249]
	v_lshl_add_u64 v[248:249], v[248:249], 0, v[246:247]
	v_ashrrev_i32_e32 v243, 31, v242
	v_ashrrev_i32_e32 v245, 31, v244
	v_lshlrev_b64 v[242:243], 14, v[242:243]
	v_lshlrev_b64 v[244:245], 14, v[244:245]
	v_lshl_add_u64 v[242:243], v[248:249], 0, v[242:243]
	v_lshl_add_u64 v[244:245], v[248:249], 0, v[244:245]
	global_load_dwordx4 v[232:235], v[242:243], off
	global_load_dwordx4 v[236:239], v[244:245], off
	v_and_b32_e32 v70, 15, v222
	s_bfe_u32 s72, s10, 0x20007
	v_lshlrev_b32_e32 v70, 3, v70
	s_lshl_b32 s72, s72, 7
	v_add_u32_e32 v70, s72, v70
	v_lshlrev_b32_e32 v71, 2, v70
	v_add_u32_e32 v72, 0x1000, v71
	v_add_u32_e32 v73, 0x2000, v71
	v_add_u32_e32 v74, 0x3000, v71
	global_load_dwordx4 v[140:143], v71, s[62:63] offset:2048
	global_load_dwordx4 v[144:147], v71, s[62:63] offset:2064
	global_load_dwordx4 v[148:151], v72, s[62:63] offset:2048
	global_load_dwordx4 v[152:155], v72, s[62:63] offset:2064
	global_load_dwordx4 v[156:159], v73, s[62:63] offset:2048
	global_load_dwordx4 v[160:163], v73, s[62:63] offset:2064
	global_load_dwordx4 v[164:167], v74, s[62:63] offset:2048
	global_load_dwordx4 v[168:171], v74, s[62:63] offset:2064
	global_load_dwordx4 v[224:227], v71, s[64:65] offset:2048
	global_load_dwordx4 v[228:231], v71, s[64:65] offset:2064
	s_ashr_i32 s74, s10, 9
	s_ashr_i32 s75, s74, 31
	s_lshl_b64 s[74:75], s[74:75], 24
	s_add_u32 s74, s74, s4
	s_addc_u32 s75, s75, s5
	v_lshlrev_b32_e32 v76, 1, v70
	v_mov_b32_e32 v77, 0
	v_lshl_add_u64 v[78:79], s[74:75], 0, v[76:77]
	s_and_b32 s76, s10, 0x7f
	s_lshl_b32 s76, s76, 6
	v_lshrrev_b32_e32 v75, 4, v222
	s_movk_i32 s77, 0x800
	v_add_u32_e32 v184, s76, v75
	v_add_u32_e32 v185, -1, v184
	v_mov_b32_e32 v114, 0
	v_mov_b32_e32 v115, 0
	v_mov_b32_e32 v116, 0
	v_mov_b32_e32 v117, 0
	v_mov_b32_e32 v118, 0
	v_mov_b32_e32 v119, 0
	v_mov_b32_e32 v120, 0
	v_mov_b32_e32 v121, 0
	v_mov_b32_e32 v122, 0
	v_mov_b32_e32 v123, 0
	v_mov_b32_e32 v124, 0
	v_mov_b32_e32 v125, 0
	v_mad_i64_i32 v[186:187], s[88:89], v185, s77, v[78:79]
	v_cmp_lt_i32_e64 s[84:85], 2, v184
	s_and_saveexec_b64 s[86:87], s[84:85]
	global_load_dwordx4 v[114:117], v[186:187], off offset:-3072
	s_or_b64 exec, exec, s[86:87]
	v_cmp_lt_i32_e64 s[84:85], 1, v184
	s_and_saveexec_b64 s[86:87], s[84:85]
	global_load_dwordx4 v[118:121], v[186:187], off offset:-1024
	s_or_b64 exec, exec, s[86:87]
	v_cmp_lt_i32_e64 s[84:85], 0, v184
	s_and_saveexec_b64 s[86:87], s[84:85]
	global_load_dwordx4 v[122:125], v[186:187], off offset:1024
	s_or_b64 exec, exec, s[86:87]
	global_load_dwordx4 v[126:129], v[186:187], off offset:3072
	v_add_u32_e32 v184, 32, v184
	v_add_u32_e32 v185, -1, v184
	v_mov_b32_e32 v130, 0
	v_mov_b32_e32 v131, 0
	v_mov_b32_e32 v132, 0
	v_mov_b32_e32 v133, 0
	v_mov_b32_e32 v134, 0
	v_mov_b32_e32 v135, 0
	v_mov_b32_e32 v136, 0
	v_mov_b32_e32 v137, 0
	v_mov_b32_e32 v172, 0
	v_mov_b32_e32 v173, 0
	v_mov_b32_e32 v174, 0
	v_mov_b32_e32 v175, 0
	v_mad_i64_i32 v[186:187], s[88:89], v185, s77, v[78:79]
	v_cmp_lt_i32_e64 s[84:85], 2, v184
	s_and_saveexec_b64 s[86:87], s[84:85]
	global_load_dwordx4 v[130:133], v[186:187], off offset:-3072
	s_or_b64 exec, exec, s[86:87]
	v_cmp_lt_i32_e64 s[84:85], 1, v184
	s_and_saveexec_b64 s[86:87], s[84:85]
	global_load_dwordx4 v[134:137], v[186:187], off offset:-1024
	s_or_b64 exec, exec, s[86:87]
	v_cmp_lt_i32_e64 s[84:85], 0, v184
	s_and_saveexec_b64 s[86:87], s[84:85]
	global_load_dwordx4 v[172:175], v[186:187], off offset:1024
	s_or_b64 exec, exec, s[86:87]
	global_load_dwordx4 v[176:179], v[186:187], off offset:3072
.Lma_noissue:
	v_mov_b32_e32 v18, v222
	s_and_b32 s18, s10, 0x7f
	s_ashr_i32 s12, s10, 9
	s_nop 0
	v_cmp_lt_u32_e32 vcc, 63, v18
	s_and_saveexec_b64 s[0:1], vcc
	s_xor_b64 s[0:1], exec, s[0:1]
	s_lshl_b32 s8, s18, 6
	s_ashr_i32 s13, s12, 31
	s_or_saveexec_b64 s[14:15], s[0:1]
	s_bfe_u32 s27, s10, 0x20007
	v_and_b32_e32 v19, 63, v18
	s_ashr_i32 s11, s10, 31
	v_mov_b64_e32 v[10:11], s[12:13]
	v_mov_b64_e32 v[0:1], s[8:9]
	v_mov_b32_e32 v50, s8
	s_xor_b64 exec, exec, s[14:15]
	s_cbranch_execz .LBB0_330
; DI float wmax(float v) { for (int o = 32; o; o >>= 1) v = fmaxf(v, __shfl_xor(v, o)); return v; }
; DI float log_sigmoid(float f) { return fminf(f, 0.f) - log1pf(expf(-fabsf(f))); }
; DI float scan_sum(float v, int lane) { for (int o = 1; o < 64; o <<= 1) { float tv = __shfl_up(v, o); if (lane >= o) v += tv; } return v; }
; DI void conv_unit(const u16* __restrict__ PM, const float* __restrict__ conv_w, const float* __restrict__ conv_b, int b, int sl0, int ch, float scale, float* a8) {
;   { const float4 b0 = *(const float4*)(conv_b + ch), b1 = *(const float4*)(conv_b + ch + 4); a8[0] = b0.x; a8[1] = b0.y; a8[2] = b0.z; a8[3] = b0.w; a8[4] = b1.x; a8[5] = b1.y; a8[6] = b1.z; a8[7] = b1.w; }
; #pragma unroll
;   for (int j = 0; j < 4; ++j) {
;     const int sl = sl0 - 3 + j;
;     if (sl >= 0) {
;       const uint4 raw = *(const uint4*)(PM + ((size_t)b * SEQ + sl) * 1024 + ch);
;       float x8[8]; unpack8(raw, x8);
;       const float4 w0 = *(const float4*)(conv_w + j * 1024 + ch), w1 = *(const float4*)(conv_w + j * 1024 + ch + 4);
; DI void mlstmA_item(const Params& p, char* lds, int item) {
;     ...
;   if (wave == 0) {
;     const size_t row = (size_t)b * SEQ + c * 64 + lane;
;     const float ig = G[row * 8 + hd] + p.in[7][hd], fg = G[row * 8 + 4 + hd] + p.in[8][hd];
;     const float bc = scan_sum(log_sigmoid(fg), lane);
;     const float as = ig - bc;
;     const float gmax = wmax(as);
;     const float B = __shfl(bc, 63);
;     win[lane] = expf(as - gmax);
;     if (lane == 0) { CSC[0] = B; CSC[1] = B + gmax; }
;   }
;   for (int i = 0; i < 2; ++i) {
;     const int q = tid + 512 * i, e = q >> 3, s8 = (q & 7) * 8;
;     *(uint4*)(VTs + e * 72 + s8) = *(const uint4*)(VTm + ((size_t)(bh * 128 + e)) * SEQ + c * 64 + s8);
	s_ashr_i32 s13, s12, 31
	s_lshl_b64 s[0:1], s[12:13], 13
	s_lshl_b32 s18, s18, 6
	v_or_b32_e32 v0, s0, v18
	v_or_b32_e32 v0, s18, v0
	v_mov_b32_e32 v1, s1
	v_lshlrev_b64 v[0:1], 5, v[0:1]
	v_lshl_add_u64 v[0:1], s[52:53], 0, v[0:1]
	s_lshl_b32 s8, s27, 2
	v_lshl_add_u64 v[2:3], v[0:1], 0, s[8:9]
	v_mov_b32_e32 v1, s8
	global_load_dword v0, v[2:3], off
	global_load_dword v4, v1, s[66:67]
	s_nop 0
	global_load_dword v2, v[2:3], off offset:16
	s_nop 0
	global_load_dword v1, v1, s[36:37]
	v_add_u32_e32 v240, 0x200, v222
	s_and_b32 s73, s10, 0xffffff80
	v_lshlrev_b32_e32 v241, 4, v222
	v_ashrrev_i32_e32 v242, 3, v222
	v_ashrrev_i32_e32 v244, 3, v240
	v_and_b32_e32 v246, 0x70, v241
	v_mov_b32_e32 v247, 0
	v_add_u32_e32 v242, s73, v242
	v_add_u32_e32 v244, s73, v244
	s_and_b32 s78, s10, 0x7f
	s_lshl_b32 s78, s78, 7
	v_mov_b32_e32 v248, s78
	v_mov_b32_e32 v249, 0
	v_lshl_add_u64 v[248:249], s[6:7], 0, v[248:249]
	v_lshl_add_u64 v[248:249], v[248:249], 0, v[246:247]
	v_ashrrev_i32_e32 v243, 31, v242
	v_ashrrev_i32_e32 v245, 31, v244
	v_lshlrev_b64 v[242:243], 14, v[242:243]
	v_lshlrev_b64 v[244:245], 14, v[244:245]
	v_lshl_add_u64 v[242:243], v[248:249], 0, v[242:243]
	v_lshl_add_u64 v[244:245], v[248:249], 0, v[244:245]
	global_load_dwordx4 v[232:235], v[242:243], off
	global_load_dwordx4 v[236:239], v[244:245], off
	v_and_b32_e32 v70, 15, v222
	s_bfe_u32 s72, s10, 0x20007
	v_lshlrev_b32_e32 v70, 3, v70
	s_lshl_b32 s72, s72, 7
	v_add_u32_e32 v70, s72, v70
	v_lshlrev_b32_e32 v71, 2, v70
	v_add_u32_e32 v72, 0x1000, v71
	v_add_u32_e32 v73, 0x2000, v71
	v_add_u32_e32 v74, 0x3000, v71
	global_load_dwordx4 v[140:143], v71, s[62:63] offset:2048
	global_load_dwordx4 v[144:147], v71, s[62:63] offset:2064
	global_load_dwordx4 v[148:151], v72, s[62:63] offset:2048
	global_load_dwordx4 v[152:155], v72, s[62:63] offset:2064
	global_load_dwordx4 v[156:159], v73, s[62:63] offset:2048
	global_load_dwordx4 v[160:163], v73, s[62:63] offset:2064
	global_load_dwordx4 v[164:167], v74, s[62:63] offset:2048
	global_load_dwordx4 v[168:171], v74, s[62:63] offset:2064
	global_load_dwordx4 v[224:227], v71, s[64:65] offset:2048
	global_load_dwordx4 v[228:231], v71, s[64:65] offset:2064
	s_ashr_i32 s74, s10, 9
	s_ashr_i32 s75, s74, 31
	s_lshl_b64 s[74:75], s[74:75], 24
	s_add_u32 s74, s74, s4
	s_addc_u32 s75, s75, s5
	v_lshlrev_b32_e32 v76, 1, v70
	v_mov_b32_e32 v77, 0
	v_lshl_add_u64 v[78:79], s[74:75], 0, v[76:77]
	s_and_b32 s76, s10, 0x7f
	s_lshl_b32 s76, s76, 6
	v_lshrrev_b32_e32 v75, 4, v222
	s_movk_i32 s77, 0x800
	v_add_u32_e32 v184, s76, v75
	v_add_u32_e32 v185, -1, v184
	v_mov_b32_e32 v114, 0
	v_mov_b32_e32 v115, 0
	v_mov_b32_e32 v116, 0
	v_mov_b32_e32 v117, 0
	v_mov_b32_e32 v118, 0
	v_mov_b32_e32 v119, 0
	v_mov_b32_e32 v120, 0
	v_mov_b32_e32 v121, 0
	v_mov_b32_e32 v122, 0
	v_mov_b32_e32 v123, 0
	v_mov_b32_e32 v124, 0
	v_mov_b32_e32 v125, 0
	v_mad_i64_i32 v[186:187], s[88:89], v185, s77, v[78:79]
	v_cmp_lt_i32_e64 s[84:85], 2, v184
	s_and_saveexec_b64 s[86:87], s[84:85]
	global_load_dwordx4 v[114:117], v[186:187], off offset:-3072
	s_or_b64 exec, exec, s[86:87]
	v_cmp_lt_i32_e64 s[84:85], 1, v184
	s_and_saveexec_b64 s[86:87], s[84:85]
	global_load_dwordx4 v[118:121], v[186:187], off offset:-1024
	s_or_b64 exec, exec, s[86:87]
	v_cmp_lt_i32_e64 s[84:85], 0, v184
	s_and_saveexec_b64 s[86:87], s[84:85]
	global_load_dwordx4 v[122:125], v[186:187], off offset:1024
	s_or_b64 exec, exec, s[86:87]
	global_load_dwordx4 v[126:129], v[186:187], off offset:3072
	v_add_u32_e32 v184, 32, v184
	v_add_u32_e32 v185, -1, v184
	v_mov_b32_e32 v130, 0
	v_mov_b32_e32 v131, 0
	v_mov_b32_e32 v132, 0
	v_mov_b32_e32 v133, 0
	v_mov_b32_e32 v134, 0
	v_mov_b32_e32 v135, 0
	v_mov_b32_e32 v136, 0
	v_mov_b32_e32 v137, 0
	v_mov_b32_e32 v172, 0
	v_mov_b32_e32 v173, 0
	v_mov_b32_e32 v174, 0
	v_mov_b32_e32 v175, 0
	v_mad_i64_i32 v[186:187], s[88:89], v185, s77, v[78:79]
	v_cmp_lt_i32_e64 s[84:85], 2, v184
	s_and_saveexec_b64 s[86:87], s[84:85]
	global_load_dwordx4 v[130:133], v[186:187], off offset:-3072
	s_or_b64 exec, exec, s[86:87]
	v_cmp_lt_i32_e64 s[84:85], 1, v184
	s_and_saveexec_b64 s[86:87], s[84:85]
	global_load_dwordx4 v[134:137], v[186:187], off offset:-1024
	s_or_b64 exec, exec, s[86:87]
	v_cmp_lt_i32_e64 s[84:85], 0, v184
	s_and_saveexec_b64 s[86:87], s[84:85]
	global_load_dwordx4 v[172:175], v[186:187], off offset:1024
	s_or_b64 exec, exec, s[86:87]
	global_load_dwordx4 v[176:179], v[186:187], off offset:3072
	s_mov_b32 s0, 0xb2a5705f
	s_waitcnt vmcnt(22)
	v_add_f32_e32 v0, v0, v4
	s_waitcnt vmcnt(20)
; DI float wmax(float v) { for (int o = 32; o; o >>= 1) v = fmaxf(v, __shfl_xor(v, o)); return v; }
; DI float scan_sum(float v, int lane) { for (int o = 1; o < 64; o <<= 1) { float tv = __shfl_up(v, o); if (lane >= o) v += tv; } return v; }
; DI float log_sigmoid(float f) { return fminf(f, 0.f) - log1pf(expf(-fabsf(f))); }
; DI void mlstmA_item(const Params& p, char* lds, int item) {
;     ...
;   if (wave == 0) {
;     const size_t row = (size_t)b * SEQ + c * 64 + lane;
;     const float ig = G[row * 8 + hd] + p.in[7][hd], fg = G[row * 8 + 4 + hd] + p.in[8][hd];
;     const float bc = scan_sum(log_sigmoid(fg), lane);
;     const float as = ig - bc;
;     const float gmax = wmax(as);
;     const float B = __shfl(bc, 63);
;     win[lane] = expf(as - gmax);
;     if (lane == 0) { CSC[0] = B; CSC[1] = B + gmax; }
	v_add_f32_e32 v1, v2, v1
	v_mul_f32_e64 v2, |v1|, s23
	v_fma_f32 v3, |v1|, s23, -v2
	v_rndne_f32_e32 v5, v2
	v_fma_f32 v3, |v1|, s0, v3
	v_sub_f32_e32 v2, v2, v5
	v_add_f32_e32 v2, v2, v3
	v_exp_f32_e32 v2, v2
	v_cvt_i32_f32_e32 v3, v5
	s_mov_b32 s0, 0x42ce8ed0
	v_cmp_ngt_f32_e64 vcc, |v1|, s0
	s_mov_b32 s0, 0xc2b17218
	v_ldexp_f32 v2, v2, v3
	v_cndmask_b32_e32 v2, 0, v2, vcc
	v_cmp_nlt_f32_e64 vcc, |v1|, s0
	v_min_f32_e32 v4, 0, v1
	s_mov_b32 s0, 0x3f2aaaab
	v_cndmask_b32_e32 v1, v33, v2, vcc
	v_add_f32_e32 v5, 1.0, v1
	v_add_f32_e32 v2, -1.0, v5
	v_sub_f32_e32 v3, v2, v5
	v_add_f32_e32 v3, 1.0, v3
	v_sub_f32_e32 v2, v1, v2
	v_add_f32_e32 v6, v2, v3
	v_frexp_mant_f32_e32 v2, v5
	v_cmp_gt_f32_e32 vcc, s0, v2
	v_cvt_f64_f32_e32 v[2:3], v5
	v_frexp_exp_i32_f64_e32 v2, v[2:3]
	v_subbrev_co_u32_e32 v2, vcc, 0, v2, vcc
	v_sub_u32_e32 v3, 0, v2
	v_ldexp_f32 v5, v5, v3
	v_ldexp_f32 v3, v6, v3
	v_add_f32_e32 v6, -1.0, v5
	v_add_f32_e32 v7, 1.0, v6
	v_sub_f32_e32 v7, v5, v7
	v_add_f32_e32 v7, v3, v7
	v_add_f32_e32 v8, v6, v7
	v_sub_f32_e32 v6, v6, v8
	v_add_f32_e32 v6, v7, v6
	v_add_f32_e32 v7, 1.0, v5
	v_add_f32_e32 v9, -1.0, v7
	v_sub_f32_e32 v5, v5, v9
	v_add_f32_e32 v3, v3, v5
	v_add_f32_e32 v5, v7, v3
	v_sub_f32_e32 v7, v7, v5
	v_add_f32_e32 v3, v3, v7
	v_rcp_f32_e32 v7, v5
	v_cvt_f32_i32_e32 v2, v2
	s_mov_b32 s0, 0x3f317218
	v_mul_f32_e32 v9, v8, v7
	v_mul_f32_e32 v10, v5, v9
	v_fma_f32 v11, v9, v5, -v10
	v_fmac_f32_e32 v11, v9, v3
	v_add_f32_e32 v12, v10, v11
	v_sub_f32_e32 v13, v8, v12
	v_sub_f32_e32 v8, v8, v13
	v_sub_f32_e32 v10, v12, v10
	v_sub_f32_e32 v8, v8, v12
	v_add_f32_e32 v6, v6, v8
	v_sub_f32_e32 v8, v10, v11
	v_add_f32_e32 v6, v8, v6
	v_add_f32_e32 v8, v13, v6
	v_mul_f32_e32 v10, v7, v8
	v_mul_f32_e32 v11, v5, v10
	v_fma_f32 v5, v10, v5, -v11
	v_fmac_f32_e32 v5, v10, v3
	v_sub_f32_e32 v3, v13, v8
	v_add_f32_e32 v3, v6, v3
	v_add_f32_e32 v6, v11, v5
	v_sub_f32_e32 v12, v8, v6
	v_sub_f32_e32 v8, v8, v12
	v_sub_f32_e32 v11, v6, v11
	v_sub_f32_e32 v6, v8, v6
	v_add_f32_e32 v3, v3, v6
	v_sub_f32_e32 v5, v11, v5
	v_add_f32_e32 v3, v5, v3
	v_add_f32_e32 v5, v9, v10
	v_add_f32_e32 v3, v12, v3
	v_sub_f32_e32 v6, v5, v9
	v_mul_f32_e32 v3, v7, v3
	v_sub_f32_e32 v6, v10, v6
	v_add_f32_e32 v3, v6, v3
	v_mul_f32_e32 v9, 0x3f317218, v2
	v_add_f32_e32 v6, v5, v3
	v_fma_f32 v10, v2, s0, -v9
	v_mul_f32_e32 v7, v6, v6
	v_fmac_f32_e32 v10, 0xb102e308, v2
	v_sub_f32_e32 v2, v6, v5
	v_fmamk_f32 v8, v7, 0x3e9b6dac, v32
	v_sub_f32_e32 v2, v3, v2
	v_add_f32_e32 v3, v9, v10
	v_fmaak_f32 v8, v7, v8, 0x3f2aaada
	v_sub_f32_e32 v5, v3, v9
	v_ldexp_f32 v9, v6, 1
	v_mul_f32_e32 v6, v6, v7
	v_mul_f32_e32 v6, v6, v8
	v_add_f32_e32 v7, v9, v6
	v_sub_f32_e32 v8, v7, v9
	v_ldexp_f32 v2, v2, 1
	v_sub_f32_e32 v6, v6, v8
	v_add_f32_e32 v2, v2, v6
	v_add_f32_e32 v6, v7, v2
	v_sub_f32_e32 v7, v6, v7
	v_sub_f32_e32 v2, v2, v7
	v_add_f32_e32 v7, v3, v6
	v_sub_f32_e32 v8, v7, v3
	v_sub_f32_e32 v9, v7, v8
	v_sub_f32_e32 v5, v10, v5
	v_sub_f32_e32 v3, v3, v9
	v_sub_f32_e32 v6, v6, v8
	v_add_f32_e32 v3, v6, v3
	v_add_f32_e32 v6, v5, v2
	v_sub_f32_e32 v8, v6, v5
	v_sub_f32_e32 v9, v6, v8
	v_sub_f32_e32 v5, v5, v9
	v_sub_f32_e32 v2, v2, v8
	v_add_f32_e32 v3, v6, v3
	v_add_f32_e32 v2, v2, v5
	v_add_f32_e32 v5, v7, v3
	v_sub_f32_e32 v6, v5, v7
	v_sub_f32_e32 v3, v3, v6
	v_add_f32_e32 v2, v2, v3
	s_mov_b32 s0, 0x7f800000
	v_add_f32_e32 v2, v5, v2
	v_cmp_neq_f32_e32 vcc, s0, v1
	s_mov_b32 s0, 0x33800000
	s_nop 0
	v_cndmask_b32_e32 v2, v33, v2, vcc
	v_cmp_lt_f32_e64 vcc, |v1|, s0
	s_nop 0
	v_cndmask_b32_e32 v1, v2, v1, vcc
	v_sub_f32_e32 v1, v4, v1
	s_nop 1
	v_add_f32_dpp v1, v1, v1 row_shr:1 row_mask:0xf bank_mask:0xf
	s_nop 1
	v_add_f32_dpp v1, v1, v1 row_shr:2 row_mask:0xf bank_mask:0xf
	s_nop 1
	v_add_f32_dpp v1, v1, v1 row_shr:4 row_mask:0xf bank_mask:0xf
	s_nop 1
	v_add_f32_dpp v1, v1, v1 row_shr:8 row_mask:0xf bank_mask:0xf
	s_nop 1
	v_add_f32_dpp v1, v1, v1 row_bcast:15 row_mask:0xa bank_mask:0xf
	s_nop 1
	v_add_f32_dpp v1, v1, v1 row_bcast:31 row_mask:0xc bank_mask:0xf
	v_sub_f32_e32 v3, v0, v1
	v_mov_b32_e32 v2, v1
	v_mov_b32_e32 v5, v3
	s_nop 1
	v_max_f32_dpp v5, v5, v5 row_shr:1 row_mask:0xf bank_mask:0xf
	s_nop 1
	v_max_f32_dpp v5, v5, v5 row_shr:2 row_mask:0xf bank_mask:0xf
	s_nop 1
	v_max_f32_dpp v5, v5, v5 row_shr:4 row_mask:0xf bank_mask:0xf
	s_nop 1
	v_max_f32_dpp v5, v5, v5 row_shr:8 row_mask:0xf bank_mask:0xf
	s_nop 1
	v_max_f32_dpp v5, v5, v5 row_bcast:15 row_mask:0xa bank_mask:0xf
	s_nop 1
	v_max_f32_dpp v5, v5, v5 row_bcast:31 row_mask:0xc bank_mask:0xf
	s_nop 0
	v_readlane_b32 s1, v5, 63
	v_readlane_b32 s30, v2, 63
	v_cmp_eq_u32_e32 vcc, 0, v19
	s_mov_b32 s0, 0x3fb8aa3b
	s_nop 0
	v_mov_b32_e32 v0, s30
	v_mov_b32_e32 v1, s1
	v_sub_f32_e32 v2, v3, v1
	v_mul_f32_e32 v3, 0x3fb8aa3b, v2
	v_fma_f32 v4, v2, s0, -v3
	v_rndne_f32_e32 v5, v3
	v_fmac_f32_e32 v4, 0x32a5705f, v2
	v_sub_f32_e32 v3, v3, v5
	v_add_f32_e32 v3, v3, v4
	v_exp_f32_e32 v3, v3
	v_cvt_i32_f32_e32 v4, v5
	s_mov_b32 s0, 0xc2ce8ed0
	v_cmp_ngt_f32_e64 s[0:1], s0, v2
	v_ldexp_f32 v3, v3, v4
	s_nop 0
	v_cndmask_b32_e64 v3, 0, v3, s[0:1]
	s_mov_b32 s0, 0x42b17218
	v_cmp_nlt_f32_e64 s[0:1], s0, v2
	s_nop 1
	v_cndmask_b32_e64 v2, v33, v3, s[0:1]
	v_lshl_add_u32 v3, v19, 2, 0
	ds_write_b32 v3, v2 offset:36864
	s_and_saveexec_b64 s[0:1], vcc
	s_cbranch_execz .LBB0_329
	s_lshl_b64 s[30:31], s[10:11], 4
	s_add_u32 s30, s21, s30
	s_addc_u32 s31, s22, s31
	s_waitcnt lgkmcnt(1)
	v_add_f32_e32 v1, v1, v0
	global_store_dwordx2 v17, v[0:1], s[30:31]

; DI u16 f2bf(float x) { return (u16)(pack2(x, 0.f) & 0xffffu); }
; DI void conv_unit(const u16* __restrict__ PM, const float* __restrict__ conv_w, const float* __restrict__ conv_b, int b, int sl0, int ch, float scale, float* a8) {
;   { const float4 b0 = *(const float4*)(conv_b + ch), b1 = *(const float4*)(conv_b + ch + 4); a8[0] = b0.x; a8[1] = b0.y; a8[2] = b0.z; a8[3] = b0.w; a8[4] = b1.x; a8[5] = b1.y; a8[6] = b1.z; a8[7] = b1.w; }
; #pragma unroll
;   for (int j = 0; j < 4; ++j) {
;     const int sl = sl0 - 3 + j;
;     if (sl >= 0) {
;       const uint4 raw = *(const uint4*)(PM + ((size_t)b * SEQ + sl) * 1024 + ch);
;       float x8[8]; unpack8(raw, x8);
;       const float4 w0 = *(const float4*)(conv_w + j * 1024 + ch), w1 = *(const float4*)(conv_w + j * 1024 + ch + 4);
;       a8[0] += w0.x * x8[0]; a8[1] += w0.y * x8[1]; a8[2] += w0.z * x8[2]; a8[3] += w0.w * x8[3];
;       a8[4] += w1.x * x8[4]; a8[5] += w1.y * x8[5]; a8[6] += w1.z * x8[6]; a8[7] += w1.w * x8[7];
;     }
;   }
; #pragma unroll
;   for (int e = 0; e < 8; ++e) { const float v = a8[e]; a8[e] = scale * v * __builtin_amdgcn_rcpf(1.f + __expf(-v)); }
; DI void mlstmA_item(const Params& p, char* lds, int item) {
;     ...
;   for (int i = 0; i < 2; ++i) {
;     const int q = tid + 512 * i, e = q >> 3, s8 = (q & 7) * 8;
;     *(uint4*)(VTs + e * 72 + s8) = *(const uint4*)(VTm + ((size_t)(bh * 128 + e)) * SEQ + c * 64 + s8);
;   }
;   __syncthreads();
; #pragma unroll 1
;   for (int i = 0; i < 2; ++i) {
;     const int cgk = tid & 15, t = (tid >> 4) + 32 * i;
;     float a8[8];
;     conv_unit(PM, p.in[5], p.in[6], b, c * 64 + t, 512 + hd * 128 + cgk * 8, 0.08838834764831845f, a8);
;     const float w = win[t];
; #pragma unroll
;     for (int e = 0; e < 8; ++e) KTs[(cgk * 8 + e) * 72 + t] = f2bf(a8[e] * w);
.LBB0_330:
	s_or_b64 exec, exec, s[14:15]
	v_add_u32_e32 v4, 0x200, v18
	s_and_b32 s0, s10, 0xffffff80
	v_lshlrev_b32_e32 v2, 4, v18
	v_ashrrev_i32_e32 v9, 3, v18
	v_ashrrev_i32_e32 v14, 3, v4
	v_and_b32_e32 v16, 0x70, v2
	v_add_u32_e32 v2, s0, v9
	v_add_u32_e32 v4, s0, v14
	v_lshl_add_u64 v[0:1], v[0:1], 1, s[6:7]
	v_ashrrev_i32_e32 v3, 31, v2
	v_ashrrev_i32_e32 v5, 31, v4
	v_lshl_add_u64 v[0:1], v[0:1], 0, v[16:17]
	v_lshlrev_b64 v[2:3], 14, v[2:3]
	v_lshlrev_b64 v[4:5], 14, v[4:5]
	v_lshl_add_u64 v[2:3], v[0:1], 0, v[2:3]
	v_lshl_add_u64 v[4:5], v[0:1], 0, v[4:5]
	v_lshlrev_b32_e32 v8, 3, v18
	v_and_b32_e32 v22, 0x78, v8
	v_add_u32_e32 v8, 0, v16
	v_lshl_or_b32 v15, s27, 7, v22
	v_mad_u64_u32 v[12:13], s[0:1], v9, s26, v[8:9]
	v_lshlrev_b32_e32 v16, 2, v15
	v_mad_u64_u32 v[8:9], s[0:1], v14, s26, v[8:9]
	v_lshlrev_b64 v[10:11], 24, v[10:11]
	v_lshl_add_u64 v[10:11], s[4:5], 0, v[10:11]
	v_mov_b32_e32 v13, v17
	s_mov_b64 s[0:1], 0x1800
	v_ashrrev_i32_e32 v51, 4, v18
	v_mad_u32_u24 v52, v22, s26, 0
	s_mov_b32 s8, 0
	s_waitcnt vmcnt(19)
	ds_write_b128 v12, v[232:235] offset:18432
	s_waitcnt vmcnt(18)
	ds_write_b128 v8, v[236:239] offset:18432
	s_waitcnt lgkmcnt(0)
	s_barrier
	s_waitcnt vmcnt(0)
	v_mov_b32_e32 v197, v51
	v_lshlrev_b32_e32 v196, 2, v197
	ds_read_b32 v196, v196 offset:36864
	v_lshl_add_u32 v198, v197, 1, v52
	v_lshlrev_b32_e32 v188, 16, v114
	v_and_b32_e32 v189, 0xffff0000, v114
	v_lshlrev_b32_e32 v190, 16, v115
	v_and_b32_e32 v191, 0xffff0000, v115
	v_lshlrev_b32_e32 v192, 16, v116
	v_and_b32_e32 v193, 0xffff0000, v116
	v_lshlrev_b32_e32 v194, 16, v117
	v_and_b32_e32 v195, 0xffff0000, v117
	v_pk_fma_f32 v[204:205], v[140:141], v[188:189], v[224:225]
	v_pk_fma_f32 v[206:207], v[142:143], v[190:191], v[226:227]
	v_pk_fma_f32 v[208:209], v[144:145], v[192:193], v[228:229]
	v_pk_fma_f32 v[210:211], v[146:147], v[194:195], v[230:231]
	v_lshlrev_b32_e32 v188, 16, v118
	v_and_b32_e32 v189, 0xffff0000, v118
	v_lshlrev_b32_e32 v190, 16, v119
	v_and_b32_e32 v191, 0xffff0000, v119
	v_lshlrev_b32_e32 v192, 16, v120
	v_and_b32_e32 v193, 0xffff0000, v120
	v_lshlrev_b32_e32 v194, 16, v121
	v_and_b32_e32 v195, 0xffff0000, v121
	v_pk_fma_f32 v[204:205], v[148:149], v[188:189], v[204:205]
	v_pk_fma_f32 v[206:207], v[150:151], v[190:191], v[206:207]
	v_pk_fma_f32 v[208:209], v[152:153], v[192:193], v[208:209]
	v_pk_fma_f32 v[210:211], v[154:155], v[194:195], v[210:211]
	v_lshlrev_b32_e32 v188, 16, v122
	v_and_b32_e32 v189, 0xffff0000, v122
	v_lshlrev_b32_e32 v190, 16, v123
	v_and_b32_e32 v191, 0xffff0000, v123
	v_lshlrev_b32_e32 v192, 16, v124
	v_and_b32_e32 v193, 0xffff0000, v124
	v_lshlrev_b32_e32 v194, 16, v125
	v_and_b32_e32 v195, 0xffff0000, v125
	v_pk_fma_f32 v[204:205], v[156:157], v[188:189], v[204:205]
	v_pk_fma_f32 v[206:207], v[158:159], v[190:191], v[206:207]
	v_pk_fma_f32 v[208:209], v[160:161], v[192:193], v[208:209]
	v_pk_fma_f32 v[210:211], v[162:163], v[194:195], v[210:211]
	v_lshlrev_b32_e32 v188, 16, v126
	v_and_b32_e32 v189, 0xffff0000, v126
	v_lshlrev_b32_e32 v190, 16, v127
	v_and_b32_e32 v191, 0xffff0000, v127
	v_lshlrev_b32_e32 v192, 16, v128
	v_and_b32_e32 v193, 0xffff0000, v128
	v_lshlrev_b32_e32 v194, 16, v129
	v_and_b32_e32 v195, 0xffff0000, v129
	v_pk_fma_f32 v[204:205], v[164:165], v[188:189], v[204:205]
	v_pk_fma_f32 v[206:207], v[166:167], v[190:191], v[206:207]
	v_pk_fma_f32 v[208:209], v[168:169], v[192:193], v[208:209]
	v_pk_fma_f32 v[210:211], v[170:171], v[194:195], v[210:211]
	v_mul_f32_e32 v212, 0xbfb8aa3b, v204
	v_mul_f32_e32 v213, 0xbfb8aa3b, v205
	v_mul_f32_e32 v214, 0xbfb8aa3b, v206
	v_mul_f32_e32 v215, 0xbfb8aa3b, v207
	v_mul_f32_e32 v216, 0xbfb8aa3b, v208
	v_mul_f32_e32 v217, 0xbfb8aa3b, v209
	v_mul_f32_e32 v218, 0xbfb8aa3b, v210
	v_mul_f32_e32 v219, 0xbfb8aa3b, v211
	v_mul_f32_e32 v188, 0x3db504f3, v204
	v_mul_f32_e32 v189, 0x3db504f3, v205
	v_mul_f32_e32 v190, 0x3db504f3, v206
	v_mul_f32_e32 v191, 0x3db504f3, v207
	v_mul_f32_e32 v192, 0x3db504f3, v208
	v_mul_f32_e32 v193, 0x3db504f3, v209
	v_mul_f32_e32 v194, 0x3db504f3, v210
	v_mul_f32_e32 v195, 0x3db504f3, v211
	v_exp_f32_e32 v212, v212
	v_exp_f32_e32 v213, v213
	v_exp_f32_e32 v214, v214
	v_exp_f32_e32 v215, v215
	v_exp_f32_e32 v216, v216
	v_exp_f32_e32 v217, v217
	v_exp_f32_e32 v218, v218
	v_exp_f32_e32 v219, v219
	v_add_f32_e32 v212, 1.0, v212
	v_add_f32_e32 v213, 1.0, v213
	v_add_f32_e32 v214, 1.0, v214
	v_add_f32_e32 v215, 1.0, v215
	v_add_f32_e32 v216, 1.0, v216
	v_add_f32_e32 v217, 1.0, v217
	v_add_f32_e32 v218, 1.0, v218
	v_add_f32_e32 v219, 1.0, v219
	v_rcp_f32_e32 v212, v212
	v_rcp_f32_e32 v213, v213
	v_rcp_f32_e32 v214, v214
	v_rcp_f32_e32 v215, v215
	v_rcp_f32_e32 v216, v216
	v_rcp_f32_e32 v217, v217
	v_rcp_f32_e32 v218, v218
	v_rcp_f32_e32 v219, v219
	v_mul_f32_e32 v188, v188, v212
	v_mul_f32_e32 v189, v189, v213
	v_mul_f32_e32 v190, v190, v214
	v_mul_f32_e32 v191, v191, v215
	v_mul_f32_e32 v192, v192, v216
	v_mul_f32_e32 v193, v193, v217
	v_mul_f32_e32 v194, v194, v218
	v_mul_f32_e32 v195, v195, v219
	s_waitcnt lgkmcnt(0)
; DI u16 f2bf(float x) { return (u16)(pack2(x, 0.f) & 0xffffu); }
; DI void conv_unit(const u16* __restrict__ PM, const float* __restrict__ conv_w, const float* __restrict__ conv_b, int b, int sl0, int ch, float scale, float* a8) {
;   { const float4 b0 = *(const float4*)(conv_b + ch), b1 = *(const float4*)(conv_b + ch + 4); a8[0] = b0.x; a8[1] = b0.y; a8[2] = b0.z; a8[3] = b0.w; a8[4] = b1.x; a8[5] = b1.y; a8[6] = b1.z; a8[7] = b1.w; }
; #pragma unroll
;   for (int j = 0; j < 4; ++j) {
;     const int sl = sl0 - 3 + j;
;     if (sl >= 0) {
;       const uint4 raw = *(const uint4*)(PM + ((size_t)b * SEQ + sl) * 1024 + ch);
;       float x8[8]; unpack8(raw, x8);
;       const float4 w0 = *(const float4*)(conv_w + j * 1024 + ch), w1 = *(const float4*)(conv_w + j * 1024 + ch + 4);
;       a8[0] += w0.x * x8[0]; a8[1] += w0.y * x8[1]; a8[2] += w0.z * x8[2]; a8[3] += w0.w * x8[3];
;       a8[4] += w1.x * x8[4]; a8[5] += w1.y * x8[5]; a8[6] += w1.z * x8[6]; a8[7] += w1.w * x8[7];
;     }
;   }
; #pragma unroll
;   for (int e = 0; e < 8; ++e) { const float v = a8[e]; a8[e] = scale * v * __builtin_amdgcn_rcpf(1.f + __expf(-v)); }
; DI void mlstmA_item(const Params& p, char* lds, int item) {
;     ...
; #pragma unroll 1
;   for (int i = 0; i < 2; ++i) {
;     const int cgk = tid & 15, t = (tid >> 4) + 32 * i;
;     float a8[8];
;     conv_unit(PM, p.in[5], p.in[6], b, c * 64 + t, 512 + hd * 128 + cgk * 8, 0.08838834764831845f, a8);
;     const float w = win[t];
; #pragma unroll
;     for (int e = 0; e < 8; ++e) KTs[(cgk * 8 + e) * 72 + t] = f2bf(a8[e] * w);
	v_mul_f32_e32 v188, v196, v188
	v_mul_f32_e32 v189, v196, v189
	v_mul_f32_e32 v190, v196, v190
	v_mul_f32_e32 v191, v196, v191
	v_mul_f32_e32 v192, v196, v192
	v_mul_f32_e32 v193, v196, v193
	v_mul_f32_e32 v194, v196, v194
	v_mul_f32_e32 v195, v196, v195
	v_cvt_pk_bf16_f32 v188, v188, s77
	v_cvt_pk_bf16_f32 v189, v189, s77
	v_cvt_pk_bf16_f32 v190, v190, s77
	v_cvt_pk_bf16_f32 v191, v191, s77
	v_cvt_pk_bf16_f32 v192, v192, s77
	v_cvt_pk_bf16_f32 v193, v193, s77
	v_cvt_pk_bf16_f32 v194, v194, s77
	v_cvt_pk_bf16_f32 v195, v195, s77
	ds_write_b16 v198, v188
	ds_write_b16 v198, v189 offset:144
	ds_write_b16 v198, v190 offset:288
	ds_write_b16 v198, v191 offset:432
	ds_write_b16 v198, v192 offset:576
	ds_write_b16 v198, v193 offset:720
	ds_write_b16 v198, v194 offset:864
	ds_write_b16 v198, v195 offset:1008
	v_add_u32_e32 v197, 32, v51
	v_lshlrev_b32_e32 v196, 2, v197
	ds_read_b32 v196, v196 offset:36864
	v_lshl_add_u32 v198, v197, 1, v52
	v_lshlrev_b32_e32 v188, 16, v130
	v_and_b32_e32 v189, 0xffff0000, v130
	v_lshlrev_b32_e32 v190, 16, v131
	v_and_b32_e32 v191, 0xffff0000, v131
	v_lshlrev_b32_e32 v192, 16, v132
	v_and_b32_e32 v193, 0xffff0000, v132
	v_lshlrev_b32_e32 v194, 16, v133
	v_and_b32_e32 v195, 0xffff0000, v133
	v_pk_fma_f32 v[204:205], v[140:141], v[188:189], v[224:225]
	v_pk_fma_f32 v[206:207], v[142:143], v[190:191], v[226:227]
	v_pk_fma_f32 v[208:209], v[144:145], v[192:193], v[228:229]
	v_pk_fma_f32 v[210:211], v[146:147], v[194:195], v[230:231]
	v_lshlrev_b32_e32 v188, 16, v134
	v_and_b32_e32 v189, 0xffff0000, v134
	v_lshlrev_b32_e32 v190, 16, v135
	v_and_b32_e32 v191, 0xffff0000, v135
	v_lshlrev_b32_e32 v192, 16, v136
	v_and_b32_e32 v193, 0xffff0000, v136
	v_lshlrev_b32_e32 v194, 16, v137
	v_and_b32_e32 v195, 0xffff0000, v137
	v_pk_fma_f32 v[204:205], v[148:149], v[188:189], v[204:205]
	v_pk_fma_f32 v[206:207], v[150:151], v[190:191], v[206:207]
	v_pk_fma_f32 v[208:209], v[152:153], v[192:193], v[208:209]
	v_pk_fma_f32 v[210:211], v[154:155], v[194:195], v[210:211]
	v_lshlrev_b32_e32 v188, 16, v172
	v_and_b32_e32 v189, 0xffff0000, v172
	v_lshlrev_b32_e32 v190, 16, v173
	v_and_b32_e32 v191, 0xffff0000, v173
	v_lshlrev_b32_e32 v192, 16, v174
	v_and_b32_e32 v193, 0xffff0000, v174
	v_lshlrev_b32_e32 v194, 16, v175
	v_and_b32_e32 v195, 0xffff0000, v175
	v_pk_fma_f32 v[204:205], v[156:157], v[188:189], v[204:205]
	v_pk_fma_f32 v[206:207], v[158:159], v[190:191], v[206:207]
	v_pk_fma_f32 v[208:209], v[160:161], v[192:193], v[208:209]
	v_pk_fma_f32 v[210:211], v[162:163], v[194:195], v[210:211]
	v_lshlrev_b32_e32 v188, 16, v176
	v_and_b32_e32 v189, 0xffff0000, v176
	v_lshlrev_b32_e32 v190, 16, v177
	v_and_b32_e32 v191, 0xffff0000, v177
	v_lshlrev_b32_e32 v192, 16, v178
	v_and_b32_e32 v193, 0xffff0000, v178
	v_lshlrev_b32_e32 v194, 16, v179
	v_and_b32_e32 v195, 0xffff0000, v179
	v_pk_fma_f32 v[204:205], v[164:165], v[188:189], v[204:205]
	v_pk_fma_f32 v[206:207], v[166:167], v[190:191], v[206:207]
	v_pk_fma_f32 v[208:209], v[168:169], v[192:193], v[208:209]
	v_pk_fma_f32 v[210:211], v[170:171], v[194:195], v[210:211]
	v_mul_f32_e32 v212, 0xbfb8aa3b, v204
	v_mul_f32_e32 v213, 0xbfb8aa3b, v205
	v_mul_f32_e32 v214, 0xbfb8aa3b, v206
	v_mul_f32_e32 v215, 0xbfb8aa3b, v207
	v_mul_f32_e32 v216, 0xbfb8aa3b, v208
	v_mul_f32_e32 v217, 0xbfb8aa3b, v209
	v_mul_f32_e32 v218, 0xbfb8aa3b, v210
	v_mul_f32_e32 v219, 0xbfb8aa3b, v211
	v_mul_f32_e32 v188, 0x3db504f3, v204
	v_mul_f32_e32 v189, 0x3db504f3, v205
	v_mul_f32_e32 v190, 0x3db504f3, v206
	v_mul_f32_e32 v191, 0x3db504f3, v207
	v_mul_f32_e32 v192, 0x3db504f3, v208
	v_mul_f32_e32 v193, 0x3db504f3, v209
	v_mul_f32_e32 v194, 0x3db504f3, v210
	v_mul_f32_e32 v195, 0x3db504f3, v211
	v_exp_f32_e32 v212, v212
	v_exp_f32_e32 v213, v213
	v_exp_f32_e32 v214, v214
	v_exp_f32_e32 v215, v215
	v_exp_f32_e32 v216, v216
	v_exp_f32_e32 v217, v217
	v_exp_f32_e32 v218, v218
	v_exp_f32_e32 v219, v219
	v_add_f32_e32 v212, 1.0, v212
	v_add_f32_e32 v213, 1.0, v213
	v_add_f32_e32 v214, 1.0, v214
	v_add_f32_e32 v215, 1.0, v215
	v_add_f32_e32 v216, 1.0, v216
	v_add_f32_e32 v217, 1.0, v217
	v_add_f32_e32 v218, 1.0, v218
	v_add_f32_e32 v219, 1.0, v219
	v_rcp_f32_e32 v212, v212
	v_rcp_f32_e32 v213, v213
	v_rcp_f32_e32 v214, v214
	v_rcp_f32_e32 v215, v215
	v_rcp_f32_e32 v216, v216
	v_rcp_f32_e32 v217, v217
	v_rcp_f32_e32 v218, v218
	v_rcp_f32_e32 v219, v219
	v_mul_f32_e32 v188, v188, v212
	v_mul_f32_e32 v189, v189, v213
	v_mul_f32_e32 v190, v190, v214
	v_mul_f32_e32 v191, v191, v215
	v_mul_f32_e32 v192, v192, v216
	v_mul_f32_e32 v193, v193, v217
	v_mul_f32_e32 v194, v194, v218
	v_mul_f32_e32 v195, v195, v219
	s_waitcnt lgkmcnt(0)
	v_mul_f32_e32 v188, v196, v188
	v_mul_f32_e32 v189, v196, v189
	v_mul_f32_e32 v190, v196, v190
	v_mul_f32_e32 v191, v196, v191
	v_mul_f32_e32 v192, v196, v192
	v_mul_f32_e32 v193, v196, v193
	v_mul_f32_e32 v194, v196, v194
	v_mul_f32_e32 v195, v196, v195
	v_cvt_pk_bf16_f32 v188, v188, s77
	v_cvt_pk_bf16_f32 v189, v189, s77
	v_cvt_pk_bf16_f32 v190, v190, s77
	v_cvt_pk_bf16_f32 v191, v191, s77
	v_cvt_pk_bf16_f32 v192, v192, s77
	v_cvt_pk_bf16_f32 v193, v193, s77
	v_cvt_pk_bf16_f32 v194, v194, s77
	v_cvt_pk_bf16_f32 v195, v195, s77
	ds_write_b16 v198, v188
	ds_write_b16 v198, v189 offset:144
	ds_write_b16 v198, v190 offset:288
	ds_write_b16 v198, v191 offset:432
	ds_write_b16 v198, v192 offset:576
	ds_write_b16 v198, v193 offset:720
	ds_write_b16 v198, v194 offset:864
	ds_write_b16 v198, v195 offset:1008
